# adds: expert GEMM skips the MFMAs of the all-zero padded half of row tile 8; prologue modulation GEMV k-loop double-buffered (16 loads in flight)
# speedup vs baseline: 1.0053x; 1.0053x over previous
; DEV void phase_prologue_a(const Frame& F0) {
;     ...
;         const int k0 = F.wave * 128;
; #pragma unroll 8
;         for (int k = 0; k < 128; ++k) { const float wv = w[(size_t)(k0 + k) * 6144];
; #pragma unroll
;             for (int r = 0; r < NR; ++r) acc[r] += sv[r * 1024 + k0 + k] * wv; }
; #pragma unroll
;         for (int r = 0; r < NR; ++r) part[(F.wave * NR + r) * 64 + F.lane] = acc[r];
.Lgemv_loop:
	v_lshl_add_u64 v[12:13], v[4:5], 0, s[4:5]
	v_add_co_u32_e64 v14, s[0:1], s11, v12
	global_load_dword v72, v[12:13], off
	s_nop 0
	v_addc_co_u32_e64 v15, s[0:1], 0, v13, s[0:1]
	v_add_co_u32_e64 v20, s[0:1], s14, v12
	v_mov_b32_e32 v90, s7
	s_nop 0
	v_addc_co_u32_e64 v21, s[0:1], 0, v13, s[0:1]
	v_add_co_u32_e64 v22, s[0:1], s15, v12
	s_add_u32 s4, s4, 0x30000
	s_nop 0
	v_addc_co_u32_e64 v23, s[0:1], 0, v13, s[0:1]
	v_add_co_u32_e64 v24, s[0:1], s16, v12
	s_addc_u32 s5, s5, 0
	s_nop 0
	v_addc_co_u32_e64 v25, s[0:1], 0, v13, s[0:1]
	v_add_co_u32_e64 v26, s[0:1], s17, v12
	s_add_i32 s7, s7, 32
	s_nop 0
	v_addc_co_u32_e64 v27, s[0:1], 0, v13, s[0:1]
	v_add_co_u32_e64 v28, s[0:1], s18, v12
	s_cmp_eq_u32 s4, 0x300000
	s_nop 0
	v_addc_co_u32_e64 v29, s[0:1], 0, v13, s[0:1]
	v_add_co_u32_e64 v12, s[0:1], s19, v12
	s_nop 1
	v_addc_co_u32_e64 v13, s[0:1], 0, v13, s[0:1]
	global_load_dword v74, v[14:15], off
	global_load_dword v76, v[20:21], off
	global_load_dword v78, v[22:23], off
	global_load_dword v80, v[24:25], off
	global_load_dword v84, v[26:27], off
	global_load_dword v86, v[28:29], off
	global_load_dword v88, v[12:13], off
	ds_read_b128 v[12:15], v11
	ds_read_b128 v[20:23], v11 offset:16
	ds_read_b128 v[24:27], v11 offset:4096
	ds_read_b128 v[28:31], v11 offset:4112
	ds_read_b128 v[32:35], v11 offset:8192
	ds_read_b128 v[36:39], v11 offset:8208
	ds_read_b128 v[40:43], v11 offset:12288
	ds_read_b128 v[44:47], v11 offset:12304
	ds_read_b128 v[48:51], v11 offset:16384
	ds_read_b128 v[52:55], v11 offset:16400
	s_waitcnt lgkmcnt(9)
	v_mov_b32_e32 v70, v12
	s_waitcnt lgkmcnt(7)
	v_mov_b32_e32 v71, v24
	v_mov_b32_e32 v24, v13
	v_mov_b32_e32 v12, v14
	v_mov_b32_e32 v13, v26
	v_mov_b32_e32 v26, v15
	s_waitcnt lgkmcnt(5)
	v_mov_b32_e32 v14, v32
	s_waitcnt lgkmcnt(3)
	v_mov_b32_e32 v15, v40
	v_mov_b32_e32 v40, v33
	v_mov_b32_e32 v32, v34
	v_mov_b32_e32 v33, v42
	v_mov_b32_e32 v42, v35
	v_mov_b32_e32 v34, v20
	v_mov_b32_e32 v35, v28
	v_mov_b32_e32 v28, v21
	v_mov_b32_e32 v20, v22
	v_mov_b32_e32 v21, v30
	v_mov_b32_e32 v30, v23
	v_mov_b32_e32 v22, v36
	s_waitcnt lgkmcnt(2)
	v_mov_b32_e32 v23, v44
	v_mov_b32_e32 v44, v37
	v_mov_b32_e32 v36, v38
	v_mov_b32_e32 v37, v46
	v_mov_b32_e32 v46, v39
	s_waitcnt vmcnt(15)
	v_pk_fma_f32 v[6:7], v[16:17], v[70:71], v[6:7] op_sel_hi:[0,1,1]
	v_pk_fma_f32 v[8:9], v[16:17], v[14:15], v[8:9] op_sel_hi:[0,1,1]
	s_waitcnt lgkmcnt(1)
	v_fmac_f32_e32 v10, v16, v48
	s_waitcnt vmcnt(14)
	v_pk_fma_f32 v[6:7], v[56:57], v[24:25], v[6:7] op_sel_hi:[0,1,1]
	v_pk_fma_f32 v[8:9], v[56:57], v[40:41], v[8:9] op_sel_hi:[0,1,1]
	v_fmac_f32_e32 v10, v56, v49
	s_waitcnt vmcnt(13)
	v_pk_fma_f32 v[6:7], v[58:59], v[12:13], v[6:7] op_sel_hi:[0,1,1]
	v_pk_fma_f32 v[8:9], v[58:59], v[32:33], v[8:9] op_sel_hi:[0,1,1]
	v_fmac_f32_e32 v10, v58, v50
	s_waitcnt vmcnt(12)
	v_pk_fma_f32 v[6:7], v[60:61], v[26:27], v[6:7] op_sel_hi:[0,1,1]
	v_pk_fma_f32 v[8:9], v[60:61], v[42:43], v[8:9] op_sel_hi:[0,1,1]
	v_fmac_f32_e32 v10, v60, v51
	s_waitcnt vmcnt(11)
	v_pk_fma_f32 v[6:7], v[62:63], v[34:35], v[6:7] op_sel_hi:[0,1,1]
	v_pk_fma_f32 v[8:9], v[62:63], v[22:23], v[8:9] op_sel_hi:[0,1,1]
	s_waitcnt lgkmcnt(0)
	v_fmac_f32_e32 v10, v62, v52
	s_waitcnt vmcnt(10)
	v_pk_fma_f32 v[6:7], v[64:65], v[28:29], v[6:7] op_sel_hi:[0,1,1]
	v_pk_fma_f32 v[8:9], v[64:65], v[44:45], v[8:9] op_sel_hi:[0,1,1]
	v_fmac_f32_e32 v10, v64, v53
	s_waitcnt vmcnt(9)
	v_pk_fma_f32 v[6:7], v[66:67], v[20:21], v[6:7] op_sel_hi:[0,1,1]
	v_pk_fma_f32 v[8:9], v[66:67], v[36:37], v[8:9] op_sel_hi:[0,1,1]
	v_fmac_f32_e32 v10, v66, v54
	s_waitcnt vmcnt(8)
	v_pk_fma_f32 v[6:7], v[68:69], v[30:31], v[6:7] op_sel_hi:[0,1,1]
	v_pk_fma_f32 v[8:9], v[68:69], v[46:47], v[8:9] op_sel_hi:[0,1,1]
	v_fmac_f32_e32 v10, v68, v55
	v_lshl_add_u64 v[12:13], v[4:5], 0, s[4:5]
	v_add_co_u32_e64 v14, s[0:1], s11, v12
	global_load_dword v16, v[12:13], off
	s_nop 0
	v_addc_co_u32_e64 v15, s[0:1], 0, v13, s[0:1]
	v_add_co_u32_e64 v20, s[0:1], s14, v12
	v_mov_b32_e32 v11, s7
	s_nop 0
	v_addc_co_u32_e64 v21, s[0:1], 0, v13, s[0:1]
	v_add_co_u32_e64 v22, s[0:1], s15, v12
	s_add_u32 s4, s4, 0x30000
	s_nop 0
	v_addc_co_u32_e64 v23, s[0:1], 0, v13, s[0:1]
	v_add_co_u32_e64 v24, s[0:1], s16, v12
	s_addc_u32 s5, s5, 0
	s_nop 0
	v_addc_co_u32_e64 v25, s[0:1], 0, v13, s[0:1]
	v_add_co_u32_e64 v26, s[0:1], s17, v12
	s_add_i32 s7, s7, 32
	s_nop 0
	v_addc_co_u32_e64 v27, s[0:1], 0, v13, s[0:1]
	v_add_co_u32_e64 v28, s[0:1], s18, v12
	s_cmp_eq_u32 s4, 0x300000
	s_nop 0
	v_addc_co_u32_e64 v29, s[0:1], 0, v13, s[0:1]
	v_add_co_u32_e64 v12, s[0:1], s19, v12
	s_nop 1
	v_addc_co_u32_e64 v13, s[0:1], 0, v13, s[0:1]
	global_load_dword v56, v[14:15], off
	global_load_dword v58, v[20:21], off
	global_load_dword v60, v[22:23], off
	global_load_dword v62, v[24:25], off
	global_load_dword v64, v[26:27], off
	global_load_dword v66, v[28:29], off
	global_load_dword v68, v[12:13], off
	ds_read_b128 v[12:15], v90
	ds_read_b128 v[20:23], v90 offset:16
	ds_read_b128 v[24:27], v90 offset:4096
	ds_read_b128 v[28:31], v90 offset:4112
	ds_read_b128 v[32:35], v90 offset:8192
	ds_read_b128 v[36:39], v90 offset:8208
	ds_read_b128 v[40:43], v90 offset:12288
	ds_read_b128 v[44:47], v90 offset:12304
	ds_read_b128 v[48:51], v90 offset:16384
	ds_read_b128 v[52:55], v90 offset:16400
	s_waitcnt lgkmcnt(9)
	v_mov_b32_e32 v70, v12
	s_waitcnt lgkmcnt(7)
	v_mov_b32_e32 v71, v24
	v_mov_b32_e32 v24, v13
	v_mov_b32_e32 v12, v14
	v_mov_b32_e32 v13, v26
	v_mov_b32_e32 v26, v15
	s_waitcnt lgkmcnt(5)
	v_mov_b32_e32 v14, v32
	s_waitcnt lgkmcnt(3)
; DEV void phase_prologue_a(const Frame& F0) {
;     ...
;         for (int k = 0; k < 128; ++k) { const float wv = w[(size_t)(k0 + k) * 6144];
; #pragma unroll
;             for (int r = 0; r < NR; ++r) acc[r] += sv[r * 1024 + k0 + k] * wv; }
	v_mov_b32_e32 v15, v40
	v_mov_b32_e32 v40, v33
	v_mov_b32_e32 v32, v34
	v_mov_b32_e32 v33, v42
	v_mov_b32_e32 v42, v35
	v_mov_b32_e32 v34, v20
	v_mov_b32_e32 v35, v28
	v_mov_b32_e32 v28, v21
	v_mov_b32_e32 v20, v22
	v_mov_b32_e32 v21, v30
	v_mov_b32_e32 v30, v23
	v_mov_b32_e32 v22, v36
	s_waitcnt lgkmcnt(2)
	v_mov_b32_e32 v23, v44
	v_mov_b32_e32 v44, v37
	v_mov_b32_e32 v36, v38
	v_mov_b32_e32 v37, v46
	v_mov_b32_e32 v46, v39
	s_waitcnt vmcnt(15)
	v_pk_fma_f32 v[6:7], v[72:73], v[70:71], v[6:7] op_sel_hi:[0,1,1]
	v_pk_fma_f32 v[8:9], v[72:73], v[14:15], v[8:9] op_sel_hi:[0,1,1]
	s_waitcnt lgkmcnt(1)
	v_fmac_f32_e32 v10, v72, v48
	s_waitcnt vmcnt(14)
	v_pk_fma_f32 v[6:7], v[74:75], v[24:25], v[6:7] op_sel_hi:[0,1,1]
	v_pk_fma_f32 v[8:9], v[74:75], v[40:41], v[8:9] op_sel_hi:[0,1,1]
	v_fmac_f32_e32 v10, v74, v49
	s_waitcnt vmcnt(13)
	v_pk_fma_f32 v[6:7], v[76:77], v[12:13], v[6:7] op_sel_hi:[0,1,1]
	v_pk_fma_f32 v[8:9], v[76:77], v[32:33], v[8:9] op_sel_hi:[0,1,1]
	v_fmac_f32_e32 v10, v76, v50
	s_waitcnt vmcnt(12)
	v_pk_fma_f32 v[6:7], v[78:79], v[26:27], v[6:7] op_sel_hi:[0,1,1]
	v_pk_fma_f32 v[8:9], v[78:79], v[42:43], v[8:9] op_sel_hi:[0,1,1]
	v_fmac_f32_e32 v10, v78, v51
	s_waitcnt vmcnt(11)
	v_pk_fma_f32 v[6:7], v[80:81], v[34:35], v[6:7] op_sel_hi:[0,1,1]
	v_pk_fma_f32 v[8:9], v[80:81], v[22:23], v[8:9] op_sel_hi:[0,1,1]
	s_waitcnt lgkmcnt(0)
	v_fmac_f32_e32 v10, v80, v52
	s_waitcnt vmcnt(10)
	v_pk_fma_f32 v[6:7], v[84:85], v[28:29], v[6:7] op_sel_hi:[0,1,1]
	v_pk_fma_f32 v[8:9], v[84:85], v[44:45], v[8:9] op_sel_hi:[0,1,1]
	v_fmac_f32_e32 v10, v84, v53
	s_waitcnt vmcnt(9)
	v_pk_fma_f32 v[6:7], v[86:87], v[20:21], v[6:7] op_sel_hi:[0,1,1]
	v_pk_fma_f32 v[8:9], v[86:87], v[36:37], v[8:9] op_sel_hi:[0,1,1]
	v_fmac_f32_e32 v10, v86, v54
	s_waitcnt vmcnt(8)
	v_pk_fma_f32 v[6:7], v[88:89], v[30:31], v[6:7] op_sel_hi:[0,1,1]
	v_pk_fma_f32 v[8:9], v[88:89], v[46:47], v[8:9] op_sel_hi:[0,1,1]
	v_fmac_f32_e32 v10, v88, v55
	s_cmp_eq_u32 s4, 0x2d0000
	s_cbranch_scc0 .Lgemv_loop
; DEV void phase_prologue_a(const Frame& F0) {
;     ...
;         const int k0 = F.wave * 128;
; #pragma unroll 8
;         for (int k = 0; k < 128; ++k) { const float wv = w[(size_t)(k0 + k) * 6144];
; #pragma unroll
;             for (int r = 0; r < NR; ++r) acc[r] += sv[r * 1024 + k0 + k] * wv; }
; #pragma unroll
;         for (int r = 0; r < NR; ++r) part[(F.wave * NR + r) * 64 + F.lane] = acc[r];
;         __syncthreads();
;         for (int i = F.tid; i < NR * 64; i += NTHREADS) { const int r = i >> 6, jj = i & 63; float s = 0.f;
; #pragma unroll
;             for (int w8 = 0; w8 < 8; ++w8) s += part[(w8 * NR + r) * 64 + jj];
;             const int col = (it % 96) * 64 + jj;
;             ((float*)(F.ws + WS_MOD))[((size_t)l * NR + r) * 6144 + col] = s + GIN(I_BMOD)[l * 6144 + col]; }
	v_lshl_add_u64 v[12:13], v[4:5], 0, s[4:5]
	v_add_co_u32_e64 v14, s[0:1], s11, v12
	global_load_dword v72, v[12:13], off
	s_nop 0
	v_addc_co_u32_e64 v15, s[0:1], 0, v13, s[0:1]
	v_add_co_u32_e64 v20, s[0:1], s14, v12
	v_mov_b32_e32 v90, s7
	s_nop 0
	v_addc_co_u32_e64 v21, s[0:1], 0, v13, s[0:1]
	v_add_co_u32_e64 v22, s[0:1], s15, v12
	s_add_u32 s4, s4, 0x30000
	s_nop 0
	v_addc_co_u32_e64 v23, s[0:1], 0, v13, s[0:1]
	v_add_co_u32_e64 v24, s[0:1], s16, v12
	s_addc_u32 s5, s5, 0
	s_nop 0
	v_addc_co_u32_e64 v25, s[0:1], 0, v13, s[0:1]
	v_add_co_u32_e64 v26, s[0:1], s17, v12
	s_add_i32 s7, s7, 32
	s_nop 0
	v_addc_co_u32_e64 v27, s[0:1], 0, v13, s[0:1]
	v_add_co_u32_e64 v28, s[0:1], s18, v12
	s_cmp_eq_u32 s4, 0x300000
	s_nop 0
	v_addc_co_u32_e64 v29, s[0:1], 0, v13, s[0:1]
	v_add_co_u32_e64 v12, s[0:1], s19, v12
	s_nop 1
	v_addc_co_u32_e64 v13, s[0:1], 0, v13, s[0:1]
	global_load_dword v74, v[14:15], off
	global_load_dword v76, v[20:21], off
	global_load_dword v78, v[22:23], off
	global_load_dword v80, v[24:25], off
	global_load_dword v84, v[26:27], off
	global_load_dword v86, v[28:29], off
	global_load_dword v88, v[12:13], off
	ds_read_b128 v[12:15], v11
	ds_read_b128 v[20:23], v11 offset:16
	ds_read_b128 v[24:27], v11 offset:4096
	ds_read_b128 v[28:31], v11 offset:4112
	ds_read_b128 v[32:35], v11 offset:8192
	ds_read_b128 v[36:39], v11 offset:8208
	ds_read_b128 v[40:43], v11 offset:12288
	ds_read_b128 v[44:47], v11 offset:12304
	ds_read_b128 v[48:51], v11 offset:16384
	ds_read_b128 v[52:55], v11 offset:16400
	s_waitcnt lgkmcnt(9)
	v_mov_b32_e32 v70, v12
	s_waitcnt lgkmcnt(7)
	v_mov_b32_e32 v71, v24
	v_mov_b32_e32 v24, v13
	v_mov_b32_e32 v12, v14
	v_mov_b32_e32 v13, v26
	v_mov_b32_e32 v26, v15
	s_waitcnt lgkmcnt(5)
	v_mov_b32_e32 v14, v32
	s_waitcnt lgkmcnt(3)
	v_mov_b32_e32 v15, v40
	v_mov_b32_e32 v40, v33
	v_mov_b32_e32 v32, v34
	v_mov_b32_e32 v33, v42
	v_mov_b32_e32 v42, v35
	v_mov_b32_e32 v34, v20
	v_mov_b32_e32 v35, v28
	v_mov_b32_e32 v28, v21
	v_mov_b32_e32 v20, v22
	v_mov_b32_e32 v21, v30
	v_mov_b32_e32 v30, v23
	v_mov_b32_e32 v22, v36
	s_waitcnt lgkmcnt(2)
	v_mov_b32_e32 v23, v44
	v_mov_b32_e32 v44, v37
	v_mov_b32_e32 v36, v38
	v_mov_b32_e32 v37, v46
	v_mov_b32_e32 v46, v39
	s_waitcnt vmcnt(15)
	v_pk_fma_f32 v[6:7], v[16:17], v[70:71], v[6:7] op_sel_hi:[0,1,1]
	v_pk_fma_f32 v[8:9], v[16:17], v[14:15], v[8:9] op_sel_hi:[0,1,1]
	s_waitcnt lgkmcnt(1)
	v_fmac_f32_e32 v10, v16, v48
	s_waitcnt vmcnt(14)
	v_pk_fma_f32 v[6:7], v[56:57], v[24:25], v[6:7] op_sel_hi:[0,1,1]
	v_pk_fma_f32 v[8:9], v[56:57], v[40:41], v[8:9] op_sel_hi:[0,1,1]
	v_fmac_f32_e32 v10, v56, v49
	s_waitcnt vmcnt(13)
	v_pk_fma_f32 v[6:7], v[58:59], v[12:13], v[6:7] op_sel_hi:[0,1,1]
	v_pk_fma_f32 v[8:9], v[58:59], v[32:33], v[8:9] op_sel_hi:[0,1,1]
	v_fmac_f32_e32 v10, v58, v50
	s_waitcnt vmcnt(12)
	v_pk_fma_f32 v[6:7], v[60:61], v[26:27], v[6:7] op_sel_hi:[0,1,1]
	v_pk_fma_f32 v[8:9], v[60:61], v[42:43], v[8:9] op_sel_hi:[0,1,1]
	v_fmac_f32_e32 v10, v60, v51
	s_waitcnt vmcnt(11)
	v_pk_fma_f32 v[6:7], v[62:63], v[34:35], v[6:7] op_sel_hi:[0,1,1]
	v_pk_fma_f32 v[8:9], v[62:63], v[22:23], v[8:9] op_sel_hi:[0,1,1]
	s_waitcnt lgkmcnt(0)
	v_fmac_f32_e32 v10, v62, v52
	s_waitcnt vmcnt(10)
	v_pk_fma_f32 v[6:7], v[64:65], v[28:29], v[6:7] op_sel_hi:[0,1,1]
	v_pk_fma_f32 v[8:9], v[64:65], v[44:45], v[8:9] op_sel_hi:[0,1,1]
	v_fmac_f32_e32 v10, v64, v53
	s_waitcnt vmcnt(9)
	v_pk_fma_f32 v[6:7], v[66:67], v[20:21], v[6:7] op_sel_hi:[0,1,1]
	v_pk_fma_f32 v[8:9], v[66:67], v[36:37], v[8:9] op_sel_hi:[0,1,1]
	v_fmac_f32_e32 v10, v66, v54
	s_waitcnt vmcnt(8)
	v_pk_fma_f32 v[6:7], v[68:69], v[30:31], v[6:7] op_sel_hi:[0,1,1]
	v_pk_fma_f32 v[8:9], v[68:69], v[46:47], v[8:9] op_sel_hi:[0,1,1]
	v_fmac_f32_e32 v10, v68, v55
	ds_read_b128 v[12:15], v90
	ds_read_b128 v[20:23], v90 offset:16
	ds_read_b128 v[24:27], v90 offset:4096
	ds_read_b128 v[28:31], v90 offset:4112
	ds_read_b128 v[32:35], v90 offset:8192
	ds_read_b128 v[36:39], v90 offset:8208
	ds_read_b128 v[40:43], v90 offset:12288
	ds_read_b128 v[44:47], v90 offset:12304
	ds_read_b128 v[48:51], v90 offset:16384
	ds_read_b128 v[52:55], v90 offset:16400
	s_waitcnt lgkmcnt(9)
	v_mov_b32_e32 v70, v12
	s_waitcnt lgkmcnt(7)
	v_mov_b32_e32 v71, v24
	v_mov_b32_e32 v24, v13
	v_mov_b32_e32 v12, v14
	v_mov_b32_e32 v13, v26
	v_mov_b32_e32 v26, v15
	s_waitcnt lgkmcnt(5)
	v_mov_b32_e32 v14, v32
	s_waitcnt lgkmcnt(3)
	v_mov_b32_e32 v15, v40
	v_mov_b32_e32 v40, v33
	v_mov_b32_e32 v32, v34
	v_mov_b32_e32 v33, v42
	v_mov_b32_e32 v42, v35
	v_mov_b32_e32 v34, v20
	v_mov_b32_e32 v35, v28
	v_mov_b32_e32 v28, v21
	v_mov_b32_e32 v20, v22
	v_mov_b32_e32 v21, v30
	v_mov_b32_e32 v30, v23
	v_mov_b32_e32 v22, v36
	s_waitcnt lgkmcnt(2)
	v_mov_b32_e32 v23, v44
	v_mov_b32_e32 v44, v37
	v_mov_b32_e32 v36, v38
	v_mov_b32_e32 v37, v46
	v_mov_b32_e32 v46, v39
	s_waitcnt vmcnt(7)
	v_pk_fma_f32 v[6:7], v[72:73], v[70:71], v[6:7] op_sel_hi:[0,1,1]
	v_pk_fma_f32 v[8:9], v[72:73], v[14:15], v[8:9] op_sel_hi:[0,1,1]
	s_waitcnt lgkmcnt(1)
	v_fmac_f32_e32 v10, v72, v48
	s_waitcnt vmcnt(6)
	v_pk_fma_f32 v[6:7], v[74:75], v[24:25], v[6:7] op_sel_hi:[0,1,1]
	v_pk_fma_f32 v[8:9], v[74:75], v[40:41], v[8:9] op_sel_hi:[0,1,1]
	v_fmac_f32_e32 v10, v74, v49
	s_waitcnt vmcnt(5)
	v_pk_fma_f32 v[6:7], v[76:77], v[12:13], v[6:7] op_sel_hi:[0,1,1]
	v_pk_fma_f32 v[8:9], v[76:77], v[32:33], v[8:9] op_sel_hi:[0,1,1]
	v_fmac_f32_e32 v10, v76, v50
	s_waitcnt vmcnt(4)
	v_pk_fma_f32 v[6:7], v[78:79], v[26:27], v[6:7] op_sel_hi:[0,1,1]
	v_pk_fma_f32 v[8:9], v[78:79], v[42:43], v[8:9] op_sel_hi:[0,1,1]
	v_fmac_f32_e32 v10, v78, v51
	s_waitcnt vmcnt(3)
	v_pk_fma_f32 v[6:7], v[80:81], v[34:35], v[6:7] op_sel_hi:[0,1,1]
	v_pk_fma_f32 v[8:9], v[80:81], v[22:23], v[8:9] op_sel_hi:[0,1,1]
	s_waitcnt lgkmcnt(0)
	v_fmac_f32_e32 v10, v80, v52
	s_waitcnt vmcnt(2)
	v_pk_fma_f32 v[6:7], v[84:85], v[28:29], v[6:7] op_sel_hi:[0,1,1]
	v_pk_fma_f32 v[8:9], v[84:85], v[44:45], v[8:9] op_sel_hi:[0,1,1]
	v_fmac_f32_e32 v10, v84, v53
	s_waitcnt vmcnt(1)
	v_pk_fma_f32 v[6:7], v[86:87], v[20:21], v[6:7] op_sel_hi:[0,1,1]
	v_pk_fma_f32 v[8:9], v[86:87], v[36:37], v[8:9] op_sel_hi:[0,1,1]
	v_fmac_f32_e32 v10, v86, v54
	s_waitcnt vmcnt(0)
	v_pk_fma_f32 v[6:7], v[88:89], v[30:31], v[6:7] op_sel_hi:[0,1,1]
	v_pk_fma_f32 v[8:9], v[88:89], v[46:47], v[8:9] op_sel_hi:[0,1,1]
	v_fmac_f32_e32 v10, v88, v55
	ds_write2st64_b32 v3, v6, v7 offset0:128 offset1:129
	ds_write2st64_b32 v3, v8, v9 offset0:130 offset1:131
	ds_write_b32 v3, v10 offset:33792
	s_waitcnt lgkmcnt(0)
	s_barrier
	s_and_saveexec_b64 s[4:5], vcc
	s_cbranch_execz .LBB0_65
	s_mul_i32 s0, s6, 0x1800
	v_or_b32_e32 v6, s8, v18
	v_add_u32_e32 v4, s0, v6
	v_ashrrev_i32_e32 v5, 31, v4
	v_ashrrev_i32_e32 v7, 31, v6
	s_mul_hi_i32 s7, s6, 5
	s_mul_i32 s6, s6, 5
	v_lshl_add_u64 v[4:5], v[4:5], 2, s[74:75]
	v_lshl_add_u64 v[6:7], v[6:7], 2, s[2:3]
	s_mov_b64 s[8:9], 0
	v_mov_b32_e32 v8, v2

; #define S_BARRIER() emu::block_barrier()
; #define WAIT_VM(n) do {} while (0)
; #define WAIT_LGKM(n) do {} while (0)
; #define SCHED_BARRIER() do {} while (0)
; #define S_BARRIER() __builtin_amdgcn_s_barrier()
; #define WAIT_VM(n) asm volatile("s_waitcnt vmcnt(" #n ")" ::: "memory")
; #define WAIT_LGKM(n) asm volatile("s_waitcnt lgkmcnt(" #n ")" ::: "memory")
; #define SCHED_BARRIER() __builtin_amdgcn_sched_barrier(0)
; #define PG8_STAGE(bufoff, gbase, voff) do { _Pragma("unroll") for (int _i = 0; _i < 2; ++_i) \
;         glds16(((const char*)(gbase) + (voff)[_i]), (lds + (bufoff) + ldsw + _i * 8192)); } while (0)
; #define PG8_STAGEA(bufoff, gptr, h, nx) do { _Pragma("unroll") for (int _i = 0; _i < 2; ++_i) { \
;         const unsigned _o = Sched::GATHER_A ? ((nx) ? goffN[h][_i] : goffC[h][_i]) : voffA[_i] + (unsigned)((h) * hstep); \
;         glds16(((const char*)(gptr) + _o), (lds + (bufoff) + ldsw + _i * 8192)); } } while (0)
; #define PG8_LDA(dst, b, h) do { _Pragma("unroll") for (int m = 0; m < 4; ++m) _Pragma("unroll") for (int k = 0; k < 2; ++k) dst[m][k] = *(const LAS bf16x8*)(lds + PG8_SA(b, h) + aoff + m * 2048 + k * 1024); } while (0)
; #define PG8_LDB(dst, b, h) do { _Pragma("unroll") for (int n = 0; n < 2; ++n) _Pragma("unroll") for (int k = 0; k < 2; ++k) dst[n][k] = *(const LAS bf16x8*)(lds + PG8_SB(b, h) + boff + n * 2048 + k * 1024); } while (0)
; #define PG8_MMA(ai, bj, At, Bt) do { SETPRIO(1); _Pragma("unroll") for (int m = 0; m < 4; ++m) _Pragma("unroll") for (int n = 0; n < 2; ++n) _Pragma("unroll") for (int k = 0; k < 2; ++k) \
;         acc[ai][bj][m][n] = mfma16(Bt[n][k], At[m][k], acc[ai][bj][m][n]); SETPRIO(0); } while (0)
; template <class Epi, class Sched>
; DEV void gemm_phase(LAS unsigned char* lds, const int K, const Sched& S, const Epi& E, const int wid, const int lane) {
;     ...
;             PG8_LDB(B0, 0, 0); PG8_LDB(B1, 0, 1); SCHED_BARRIER(); PG8_LDA(At, 0, 0); PG8_STAGEA(PG8_SA(1, 1), a1, 1, false);
;             WAIT_VM(8); WAIT_LGKM(0); S_BARRIER(); PG8_MMA(0, 0, At, B0); PG8_MMA(0, 1, At, B1); S_BARRIER(); SCHED_BARRIER();
;             PG8_LDA(At, 0, 1); PG8_STAGE(PG8_SB(0, 0), b2, voffB); PG8_STAGE(PG8_SB(0, 1), b2 + hstep, voffB); PG8_STAGEA(PG8_SA(0, 0), a2, 0, last);
;             WAIT_VM(8); WAIT_LGKM(0); S_BARRIER(); PG8_MMA(1, 0, At, B0); PG8_MMA(1, 1, At, B1); S_BARRIER(); SCHED_BARRIER();
.LBB0_1760:
	s_add_u32 s34, s6, s30
	s_addc_u32 s35, s7, s31
	s_add_u32 s36, s34, 0x37098100
	s_addc_u32 s37, s35, 0
	s_and_b64 s[34:35], s[4:5], exec
	s_cselect_b32 s37, s9, s37
	s_cselect_b32 s36, s8, s36
	s_add_u32 s60, s21, s30
	s_addc_u32 s61, s23, s31
	s_and_b64 s[34:35], s[4:5], exec
	s_cselect_b32 s35, s27, s61
	s_cselect_b32 s34, s26, s60
	s_add_i32 s60, 0, 0x10000
	v_add_u32_e32 v0, s60, v153
	s_add_i32 s62, 0, 0x14000
	ds_read_b128 v[162:165], v0
	ds_read_b128 v[166:169], v0 offset:1024
	ds_read_b128 v[170:173], v0 offset:2048
	ds_read_b128 v[174:177], v0 offset:3072
	v_add_u32_e32 v0, s62, v153
	ds_read_b128 v[178:181], v0
	ds_read_b128 v[182:185], v0 offset:1024
	ds_read_b128 v[186:189], v0 offset:2048
	ds_read_b128 v[190:193], v0 offset:3072
	v_lshl_add_u64 v[198:199], v[150:151], 0, s[30:31]
	s_add_i32 m0, s29, 0xc000
	ds_read_b128 v[194:197], v157
	ds_read_b128 v[224:227], v157 offset:1024
	ds_read_b128 v[228:231], v157 offset:2048
	ds_read_b128 v[232:235], v157 offset:3072
	ds_read_b128 v[236:239], v157 offset:4096
	ds_read_b128 v[240:243], v157 offset:5120
	ds_read_b128 v[244:247], v157 offset:6144
	ds_read_b128 v[212:215], v157 offset:7168
	global_load_lds_dwordx4 v[198:199], off
	v_lshl_add_u64 v[198:199], v[144:145], 0, s[30:31]
	s_add_i32 m0, s29, 0xe000
	s_nop 0
	global_load_lds_dwordx4 v[198:199], off
	s_waitcnt vmcnt(8)
	s_waitcnt lgkmcnt(0)
	s_barrier
	s_setprio 1
	s_waitcnt lgkmcnt(0)
	v_mfma_f32_16x16x32_bf16 v[126:129], v[162:165], v[194:197], v[126:129]
	v_mfma_f32_16x16x32_bf16 v[118:121], v[170:173], v[194:197], v[118:121]
	v_mfma_f32_16x16x32_bf16 v[110:113], v[162:165], v[228:231], v[110:113]
	v_mfma_f32_16x16x32_bf16 v[102:105], v[170:173], v[228:231], v[102:105]
	v_mfma_f32_16x16x32_bf16 v[94:97], v[162:165], v[236:239], v[94:97]
	v_mfma_f32_16x16x32_bf16 v[86:89], v[170:173], v[236:239], v[86:89]
	v_mfma_f32_16x16x32_bf16 v[78:81], v[162:165], v[244:247], v[78:81]
	v_mfma_f32_16x16x32_bf16 v[70:73], v[170:173], v[244:247], v[70:73]
	v_mfma_f32_16x16x32_bf16 v[126:129], v[166:169], v[224:227], v[126:129]
	v_mfma_f32_16x16x32_bf16 v[118:121], v[174:177], v[224:227], v[118:121]
	v_mfma_f32_16x16x32_bf16 v[110:113], v[166:169], v[232:235], v[110:113]
	v_mfma_f32_16x16x32_bf16 v[102:105], v[174:177], v[232:235], v[102:105]
	v_mfma_f32_16x16x32_bf16 v[94:97], v[166:169], v[240:243], v[94:97]
	v_mfma_f32_16x16x32_bf16 v[86:89], v[174:177], v[240:243], v[86:89]
	v_mfma_f32_16x16x32_bf16 v[78:81], v[166:169], v[212:215], v[78:81]
	v_mfma_f32_16x16x32_bf16 v[70:73], v[174:177], v[212:215], v[70:73]
	s_setprio 0
	s_setprio 1
	v_mfma_f32_16x16x32_bf16 v[122:125], v[178:181], v[194:197], v[122:125]
	v_mfma_f32_16x16x32_bf16 v[114:117], v[186:189], v[194:197], v[114:117]
	v_mfma_f32_16x16x32_bf16 v[106:109], v[178:181], v[228:231], v[106:109]
	v_mfma_f32_16x16x32_bf16 v[98:101], v[186:189], v[228:231], v[98:101]
	v_mfma_f32_16x16x32_bf16 v[90:93], v[178:181], v[236:239], v[90:93]
	v_mfma_f32_16x16x32_bf16 v[82:85], v[186:189], v[236:239], v[82:85]
	v_mfma_f32_16x16x32_bf16 v[74:77], v[178:181], v[244:247], v[74:77]
	v_mfma_f32_16x16x32_bf16 v[66:69], v[186:189], v[244:247], v[66:69]
	v_mfma_f32_16x16x32_bf16 v[122:125], v[182:185], v[224:227], v[122:125]
	v_mfma_f32_16x16x32_bf16 v[114:117], v[190:193], v[224:227], v[114:117]
	v_mfma_f32_16x16x32_bf16 v[106:109], v[182:185], v[232:235], v[106:109]
	v_mfma_f32_16x16x32_bf16 v[98:101], v[190:193], v[232:235], v[98:101]
	v_mfma_f32_16x16x32_bf16 v[90:93], v[182:185], v[240:243], v[90:93]
	v_mfma_f32_16x16x32_bf16 v[82:85], v[190:193], v[240:243], v[82:85]
	v_mfma_f32_16x16x32_bf16 v[74:77], v[182:185], v[212:215], v[74:77]
	v_mfma_f32_16x16x32_bf16 v[66:69], v[190:193], v[212:215], v[66:69]
	s_setprio 0
	s_barrier
	s_add_i32 s60, s60, s42
	v_lshl_add_u64 v[198:199], s[34:35], 0, v[134:135]
	s_mov_b32 m0, s60
	ds_read_b128 v[194:197], v157 offset:16384
	ds_read_b128 v[212:215], v157 offset:17408
	ds_read_b128 v[224:227], v157 offset:18432
	ds_read_b128 v[228:231], v157 offset:19456
	ds_read_b128 v[232:235], v157 offset:20480
	ds_read_b128 v[236:239], v157 offset:21504
	ds_read_b128 v[240:243], v157 offset:22528
	ds_read_b128 v[244:247], v157 offset:23552
	global_load_lds_dwordx4 v[198:199], off
	s_add_i32 m0, s60, 0x2000
	s_add_u32 s60, s34, 0x40000
	v_lshl_add_u64 v[248:249], s[34:35], 0, v[132:133]
	s_addc_u32 s61, s35, 0
	s_add_i32 s62, s62, s42
	global_load_lds_dwordx4 v[248:249], off
	v_lshl_add_u64 v[216:217], s[60:61], 0, v[134:135]
	s_mov_b32 m0, s62
	v_cndmask_b32_e64 v0, v136, v143, s[4:5]
	global_load_lds_dwordx4 v[216:217], off
	v_lshl_add_u64 v[216:217], s[60:61], 0, v[132:133]
	s_add_i32 m0, s62, 0x2000
	s_nop 0
	global_load_lds_dwordx4 v[216:217], off
	s_mov_b32 m0, s29
	v_lshl_add_u64 v[216:217], s[36:37], 0, v[0:1]
	global_load_lds_dwordx4 v0, s[36:37]
	v_cndmask_b32_e64 v0, v138, v158, s[4:5]
	s_mov_b32 m0, s49
	v_lshl_add_u64 v[218:219], s[36:37], 0, v[0:1]
	global_load_lds_dwordx4 v0, s[36:37]
	s_waitcnt vmcnt(8)
	s_waitcnt lgkmcnt(0)
	s_barrier
	s_setprio 1
	s_waitcnt lgkmcnt(0)
	s_cmp_eq_u32 s59, 8
	s_cbranch_scc1 .Lg4_h1
; #define S_BARRIER() emu::block_barrier()
; #define WAIT_VM(n) do {} while (0)
; #define WAIT_LGKM(n) do {} while (0)
; #define SCHED_BARRIER() do {} while (0)
; #define S_BARRIER() __builtin_amdgcn_s_barrier()
; #define WAIT_VM(n) asm volatile("s_waitcnt vmcnt(" #n ")" ::: "memory")
; #define WAIT_LGKM(n) asm volatile("s_waitcnt lgkmcnt(" #n ")" ::: "memory")
; #define SCHED_BARRIER() __builtin_amdgcn_sched_barrier(0)
; #define PG8_STAGE(bufoff, gbase, voff) do { _Pragma("unroll") for (int _i = 0; _i < 2; ++_i) \
;         glds16(((const char*)(gbase) + (voff)[_i]), (lds + (bufoff) + ldsw + _i * 8192)); } while (0)
; #define PG8_STAGEA(bufoff, gptr, h, nx) do { _Pragma("unroll") for (int _i = 0; _i < 2; ++_i) { \
;         const unsigned _o = Sched::GATHER_A ? ((nx) ? goffN[h][_i] : goffC[h][_i]) : voffA[_i] + (unsigned)((h) * hstep); \
;         glds16(((const char*)(gptr) + _o), (lds + (bufoff) + ldsw + _i * 8192)); } } while (0)
; #define PG8_LDA(dst, b, h) do { _Pragma("unroll") for (int m = 0; m < 4; ++m) _Pragma("unroll") for (int k = 0; k < 2; ++k) dst[m][k] = *(const LAS bf16x8*)(lds + PG8_SA(b, h) + aoff + m * 2048 + k * 1024); } while (0)
; #define PG8_LDB(dst, b, h) do { _Pragma("unroll") for (int n = 0; n < 2; ++n) _Pragma("unroll") for (int k = 0; k < 2; ++k) dst[n][k] = *(const LAS bf16x8*)(lds + PG8_SB(b, h) + boff + n * 2048 + k * 1024); } while (0)
; #define PG8_MMA(ai, bj, At, Bt) do { SETPRIO(1); _Pragma("unroll") for (int m = 0; m < 4; ++m) _Pragma("unroll") for (int n = 0; n < 2; ++n) _Pragma("unroll") for (int k = 0; k < 2; ++k) \
;         acc[ai][bj][m][n] = mfma16(Bt[n][k], At[m][k], acc[ai][bj][m][n]); SETPRIO(0); } while (0)
; template <class Epi, class Sched>
; DEV void gemm_phase(LAS unsigned char* lds, const int K, const Sched& S, const Epi& E, const int wid, const int lane) {
;     ...
;             WAIT_VM(8); WAIT_LGKM(0); S_BARRIER(); PG8_MMA(1, 0, At, B0); PG8_MMA(1, 1, At, B1); S_BARRIER(); SCHED_BARRIER();
;             PG8_LDB(B0, 1, 0); PG8_LDB(B1, 1, 1); SCHED_BARRIER(); PG8_LDA(At, 1, 0); PG8_STAGEA(PG8_SA(0, 1), a2, 1, last);
;             WAIT_VM(8); WAIT_LGKM(0); S_BARRIER(); PG8_MMA(0, 0, At, B0); PG8_MMA(0, 1, At, B1); S_BARRIER(); SCHED_BARRIER();
;             PG8_LDA(At, 1, 1); PG8_STAGE(PG8_SB(1, 0), b3, voffB); PG8_STAGE(PG8_SB(1, 1), b3 + hstep, voffB); PG8_STAGEA(PG8_SA(1, 0), a3, 0, last);
	v_mfma_f32_16x16x32_bf16 v[62:65], v[162:165], v[194:197], v[62:65]
	v_mfma_f32_16x16x32_bf16 v[54:57], v[170:173], v[194:197], v[54:57]
	v_mfma_f32_16x16x32_bf16 v[46:49], v[162:165], v[224:227], v[46:49]
	v_mfma_f32_16x16x32_bf16 v[38:41], v[170:173], v[224:227], v[38:41]
	v_mfma_f32_16x16x32_bf16 v[30:33], v[162:165], v[232:235], v[30:33]
	v_mfma_f32_16x16x32_bf16 v[22:25], v[170:173], v[232:235], v[22:25]
	v_mfma_f32_16x16x32_bf16 v[14:17], v[162:165], v[240:243], v[14:17]
	v_mfma_f32_16x16x32_bf16 v[6:9], v[170:173], v[240:243], v[6:9]
	v_mfma_f32_16x16x32_bf16 v[62:65], v[166:169], v[212:215], v[62:65]
	v_mfma_f32_16x16x32_bf16 v[54:57], v[174:177], v[212:215], v[54:57]
	v_mfma_f32_16x16x32_bf16 v[46:49], v[166:169], v[228:231], v[46:49]
	v_mfma_f32_16x16x32_bf16 v[38:41], v[174:177], v[228:231], v[38:41]
	v_mfma_f32_16x16x32_bf16 v[30:33], v[166:169], v[236:239], v[30:33]
	v_mfma_f32_16x16x32_bf16 v[22:25], v[174:177], v[236:239], v[22:25]
	v_mfma_f32_16x16x32_bf16 v[14:17], v[166:169], v[244:247], v[14:17]
	v_mfma_f32_16x16x32_bf16 v[6:9], v[174:177], v[244:247], v[6:9]
	s_setprio 0
	s_setprio 1
	v_mfma_f32_16x16x32_bf16 v[58:61], v[178:181], v[194:197], v[58:61]
	v_mfma_f32_16x16x32_bf16 v[50:53], v[186:189], v[194:197], v[50:53]
	v_mfma_f32_16x16x32_bf16 v[42:45], v[178:181], v[224:227], v[42:45]
	v_mfma_f32_16x16x32_bf16 v[34:37], v[186:189], v[224:227], v[34:37]
	v_mfma_f32_16x16x32_bf16 v[26:29], v[178:181], v[232:235], v[26:29]
	v_mfma_f32_16x16x32_bf16 v[18:21], v[186:189], v[232:235], v[18:21]
	v_mfma_f32_16x16x32_bf16 v[10:13], v[178:181], v[240:243], v[10:13]
	v_mfma_f32_16x16x32_bf16 v[2:5], v[186:189], v[240:243], v[2:5]
	v_mfma_f32_16x16x32_bf16 v[58:61], v[182:185], v[212:215], v[58:61]
	v_mfma_f32_16x16x32_bf16 v[50:53], v[190:193], v[212:215], v[50:53]
	v_mfma_f32_16x16x32_bf16 v[42:45], v[182:185], v[228:231], v[42:45]
	v_mfma_f32_16x16x32_bf16 v[34:37], v[190:193], v[228:231], v[34:37]
	v_mfma_f32_16x16x32_bf16 v[26:29], v[182:185], v[236:239], v[26:29]
	v_mfma_f32_16x16x32_bf16 v[18:21], v[190:193], v[236:239], v[18:21]
	v_mfma_f32_16x16x32_bf16 v[10:13], v[182:185], v[244:247], v[10:13]
	v_mfma_f32_16x16x32_bf16 v[2:5], v[190:193], v[244:247], v[2:5]
.Lg4_h1:
	s_setprio 0
	s_barrier
	s_add_i32 s60, 0, 0x18000
	v_add_u32_e32 v0, s60, v153
	s_add_i32 s61, 0, 0x1c000
	ds_read_b128 v[162:165], v0
	ds_read_b128 v[166:169], v0 offset:1024
	ds_read_b128 v[170:173], v0 offset:2048
	ds_read_b128 v[174:177], v0 offset:3072
	v_add_u32_e32 v0, s61, v153
	ds_read_b128 v[178:181], v0
	ds_read_b128 v[182:185], v0 offset:1024
	ds_read_b128 v[186:189], v0 offset:2048
	ds_read_b128 v[190:193], v0 offset:3072
	s_mov_b32 m0, s50
	v_cndmask_b32_e64 v0, v140, v159, s[4:5]
	ds_read_b128 v[194:197], v157 offset:32768
	ds_read_b128 v[212:215], v157 offset:33792
	ds_read_b128 v[224:227], v157 offset:34816
	ds_read_b128 v[228:231], v157 offset:35840
	ds_read_b128 v[232:235], v157 offset:36864
	ds_read_b128 v[236:239], v157 offset:37888
	ds_read_b128 v[240:243], v157 offset:38912
	ds_read_b128 v[244:247], v157 offset:39936
	global_load_lds_dwordx4 v0, s[36:37]
	v_cndmask_b32_e64 v0, v142, v160, s[4:5]
	s_mov_b32 m0, s51
	s_nop 0
	global_load_lds_dwordx4 v0, s[36:37]
	s_waitcnt vmcnt(8)
	s_waitcnt lgkmcnt(0)
	s_barrier
	s_setprio 1
	s_waitcnt lgkmcnt(0)
	v_mfma_f32_16x16x32_bf16 v[126:129], v[162:165], v[194:197], v[126:129]
	v_mfma_f32_16x16x32_bf16 v[118:121], v[170:173], v[194:197], v[118:121]
	v_mfma_f32_16x16x32_bf16 v[110:113], v[162:165], v[224:227], v[110:113]
	v_mfma_f32_16x16x32_bf16 v[102:105], v[170:173], v[224:227], v[102:105]
	v_mfma_f32_16x16x32_bf16 v[94:97], v[162:165], v[232:235], v[94:97]
	v_mfma_f32_16x16x32_bf16 v[86:89], v[170:173], v[232:235], v[86:89]
	v_mfma_f32_16x16x32_bf16 v[78:81], v[162:165], v[240:243], v[78:81]
	v_mfma_f32_16x16x32_bf16 v[70:73], v[170:173], v[240:243], v[70:73]
	v_mfma_f32_16x16x32_bf16 v[126:129], v[166:169], v[212:215], v[126:129]
	v_mfma_f32_16x16x32_bf16 v[118:121], v[174:177], v[212:215], v[118:121]
	v_mfma_f32_16x16x32_bf16 v[110:113], v[166:169], v[228:231], v[110:113]
	v_mfma_f32_16x16x32_bf16 v[102:105], v[174:177], v[228:231], v[102:105]
	v_mfma_f32_16x16x32_bf16 v[94:97], v[166:169], v[236:239], v[94:97]
	v_mfma_f32_16x16x32_bf16 v[86:89], v[174:177], v[236:239], v[86:89]
	v_mfma_f32_16x16x32_bf16 v[78:81], v[166:169], v[244:247], v[78:81]
	v_mfma_f32_16x16x32_bf16 v[70:73], v[174:177], v[244:247], v[70:73]
	s_setprio 0
	s_setprio 1
	v_mfma_f32_16x16x32_bf16 v[122:125], v[178:181], v[194:197], v[122:125]
	v_mfma_f32_16x16x32_bf16 v[114:117], v[186:189], v[194:197], v[114:117]
	v_mfma_f32_16x16x32_bf16 v[106:109], v[178:181], v[224:227], v[106:109]
	v_mfma_f32_16x16x32_bf16 v[98:101], v[186:189], v[224:227], v[98:101]
	v_mfma_f32_16x16x32_bf16 v[90:93], v[178:181], v[232:235], v[90:93]
	v_mfma_f32_16x16x32_bf16 v[82:85], v[186:189], v[232:235], v[82:85]
	v_mfma_f32_16x16x32_bf16 v[74:77], v[178:181], v[240:243], v[74:77]
	v_mfma_f32_16x16x32_bf16 v[66:69], v[186:189], v[240:243], v[66:69]
	v_mfma_f32_16x16x32_bf16 v[122:125], v[182:185], v[212:215], v[122:125]
	v_mfma_f32_16x16x32_bf16 v[114:117], v[190:193], v[212:215], v[114:117]
	v_mfma_f32_16x16x32_bf16 v[106:109], v[182:185], v[228:231], v[106:109]
	v_mfma_f32_16x16x32_bf16 v[98:101], v[190:193], v[228:231], v[98:101]
	v_mfma_f32_16x16x32_bf16 v[90:93], v[182:185], v[236:239], v[90:93]
	v_mfma_f32_16x16x32_bf16 v[82:85], v[190:193], v[236:239], v[82:85]
	v_mfma_f32_16x16x32_bf16 v[74:77], v[182:185], v[244:247], v[74:77]
	v_mfma_f32_16x16x32_bf16 v[66:69], v[190:193], v[244:247], v[66:69]
	s_setprio 0
	s_barrier
; #define S_BARRIER() emu::block_barrier()
; #define WAIT_VM(n) do {} while (0)
; #define WAIT_LGKM(n) do {} while (0)
; #define SCHED_BARRIER() do {} while (0)
; #define S_BARRIER() __builtin_amdgcn_s_barrier()
; #define WAIT_VM(n) asm volatile("s_waitcnt vmcnt(" #n ")" ::: "memory")
; #define WAIT_LGKM(n) asm volatile("s_waitcnt lgkmcnt(" #n ")" ::: "memory")
; #define SCHED_BARRIER() __builtin_amdgcn_sched_barrier(0)
; #define PG8_STAGE(bufoff, gbase, voff) do { _Pragma("unroll") for (int _i = 0; _i < 2; ++_i) \
;         glds16(((const char*)(gbase) + (voff)[_i]), (lds + (bufoff) + ldsw + _i * 8192)); } while (0)
; #define PG8_STAGEA(bufoff, gptr, h, nx) do { _Pragma("unroll") for (int _i = 0; _i < 2; ++_i) { \
;         const unsigned _o = Sched::GATHER_A ? ((nx) ? goffN[h][_i] : goffC[h][_i]) : voffA[_i] + (unsigned)((h) * hstep); \
;         glds16(((const char*)(gptr) + _o), (lds + (bufoff) + ldsw + _i * 8192)); } } while (0)
; #define PG8_LDA(dst, b, h) do { _Pragma("unroll") for (int m = 0; m < 4; ++m) _Pragma("unroll") for (int k = 0; k < 2; ++k) dst[m][k] = *(const LAS bf16x8*)(lds + PG8_SA(b, h) + aoff + m * 2048 + k * 1024); } while (0)
; #define PG8_MMA(ai, bj, At, Bt) do { SETPRIO(1); _Pragma("unroll") for (int m = 0; m < 4; ++m) _Pragma("unroll") for (int n = 0; n < 2; ++n) _Pragma("unroll") for (int k = 0; k < 2; ++k) \
;         acc[ai][bj][m][n] = mfma16(Bt[n][k], At[m][k], acc[ai][bj][m][n]); SETPRIO(0); } while (0)
; template <class Epi, class Sched>
; DEV void gemm_phase(LAS unsigned char* lds, const int K, const Sched& S, const Epi& E, const int wid, const int lane) {
;     ...
;             PG8_LDA(At, 1, 1); PG8_STAGE(PG8_SB(1, 0), b3, voffB); PG8_STAGE(PG8_SB(1, 1), b3 + hstep, voffB); PG8_STAGEA(PG8_SA(1, 0), a3, 0, last);
;             WAIT_VM(8); WAIT_LGKM(0); S_BARRIER(); PG8_MMA(1, 0, At, B0); PG8_MMA(1, 1, At, B1); S_BARRIER(); SCHED_BARRIER();
;         }
	s_add_i32 s4, s60, s42
	v_lshl_add_u64 v[198:199], v[198:199], 0, s[90:91]
	s_mov_b32 m0, s4
	ds_read_b128 v[194:197], v157 offset:49152
	ds_read_b128 v[212:215], v157 offset:50176
	ds_read_b128 v[224:227], v157 offset:51200
	ds_read_b128 v[228:231], v157 offset:52224
	ds_read_b128 v[232:235], v157 offset:53248
	ds_read_b128 v[236:239], v157 offset:54272
	ds_read_b128 v[240:243], v157 offset:55296
	ds_read_b128 v[244:247], v157 offset:56320
	global_load_lds_dwordx4 v[198:199], off
	s_add_i32 m0, s4, 0x2000
	s_add_u32 s4, s34, 0x40080
	v_lshl_add_u64 v[198:199], v[248:249], 0, s[90:91]
	s_addc_u32 s5, s35, 0
	s_add_i32 s34, s61, s42
	global_load_lds_dwordx4 v[198:199], off
	v_lshl_add_u64 v[198:199], s[4:5], 0, v[134:135]
	s_mov_b32 m0, s34
	s_nop 0
	global_load_lds_dwordx4 v[198:199], off
	v_lshl_add_u64 v[198:199], s[4:5], 0, v[132:133]
	s_add_i32 m0, s34, 0x2000
	s_nop 0
	global_load_lds_dwordx4 v[198:199], off
	v_lshl_add_u64 v[198:199], v[216:217], 0, s[90:91]
	s_mov_b32 m0, s52
	s_nop 0
	global_load_lds_dwordx4 v[198:199], off
	v_lshl_add_u64 v[198:199], v[218:219], 0, s[90:91]
	s_mov_b32 m0, s53
	s_nop 0
	global_load_lds_dwordx4 v[198:199], off
	s_waitcnt vmcnt(8)
	s_waitcnt lgkmcnt(0)
	s_barrier
	s_setprio 1
	s_waitcnt lgkmcnt(0)
	s_cmp_eq_u32 s59, 8
	s_cbranch_scc1 .Lg4_h3
	v_mfma_f32_16x16x32_bf16 v[62:65], v[162:165], v[194:197], v[62:65]
	v_mfma_f32_16x16x32_bf16 v[54:57], v[170:173], v[194:197], v[54:57]
	v_mfma_f32_16x16x32_bf16 v[46:49], v[162:165], v[224:227], v[46:49]
	v_mfma_f32_16x16x32_bf16 v[38:41], v[170:173], v[224:227], v[38:41]
	v_mfma_f32_16x16x32_bf16 v[30:33], v[162:165], v[232:235], v[30:33]
	v_mfma_f32_16x16x32_bf16 v[22:25], v[170:173], v[232:235], v[22:25]
	v_mfma_f32_16x16x32_bf16 v[14:17], v[162:165], v[240:243], v[14:17]
	v_mfma_f32_16x16x32_bf16 v[6:9], v[170:173], v[240:243], v[6:9]
	v_mfma_f32_16x16x32_bf16 v[62:65], v[166:169], v[212:215], v[62:65]
	v_mfma_f32_16x16x32_bf16 v[54:57], v[174:177], v[212:215], v[54:57]
	v_mfma_f32_16x16x32_bf16 v[46:49], v[166:169], v[228:231], v[46:49]
	v_mfma_f32_16x16x32_bf16 v[38:41], v[174:177], v[228:231], v[38:41]
	v_mfma_f32_16x16x32_bf16 v[30:33], v[166:169], v[236:239], v[30:33]
	v_mfma_f32_16x16x32_bf16 v[22:25], v[174:177], v[236:239], v[22:25]
	v_mfma_f32_16x16x32_bf16 v[14:17], v[166:169], v[244:247], v[14:17]
	v_mfma_f32_16x16x32_bf16 v[6:9], v[174:177], v[244:247], v[6:9]
	s_setprio 0
	s_setprio 1
	v_mfma_f32_16x16x32_bf16 v[58:61], v[178:181], v[194:197], v[58:61]
	v_mfma_f32_16x16x32_bf16 v[50:53], v[186:189], v[194:197], v[50:53]
	v_mfma_f32_16x16x32_bf16 v[42:45], v[178:181], v[224:227], v[42:45]
	v_mfma_f32_16x16x32_bf16 v[34:37], v[186:189], v[224:227], v[34:37]
	v_mfma_f32_16x16x32_bf16 v[26:29], v[178:181], v[232:235], v[26:29]
	v_mfma_f32_16x16x32_bf16 v[18:21], v[186:189], v[232:235], v[18:21]
	v_mfma_f32_16x16x32_bf16 v[10:13], v[178:181], v[240:243], v[10:13]
	v_mfma_f32_16x16x32_bf16 v[2:5], v[186:189], v[240:243], v[2:5]
	v_mfma_f32_16x16x32_bf16 v[58:61], v[182:185], v[212:215], v[58:61]
	v_mfma_f32_16x16x32_bf16 v[50:53], v[190:193], v[212:215], v[50:53]
	v_mfma_f32_16x16x32_bf16 v[42:45], v[182:185], v[228:231], v[42:45]
	v_mfma_f32_16x16x32_bf16 v[34:37], v[190:193], v[228:231], v[34:37]
	v_mfma_f32_16x16x32_bf16 v[26:29], v[182:185], v[236:239], v[26:29]
	v_mfma_f32_16x16x32_bf16 v[18:21], v[190:193], v[236:239], v[18:21]
	v_mfma_f32_16x16x32_bf16 v[10:13], v[182:185], v[244:247], v[10:13]
	v_mfma_f32_16x16x32_bf16 v[2:5], v[190:193], v[244:247], v[2:5]
.Lg4_h3:
	s_setprio 0
	s_barrier
	s_add_i32 s25, s25, 2
	s_add_u32 s30, s30, 0x100
	s_addc_u32 s31, s31, 0
	s_cmp_gt_u32 s25, 13
	s_cbranch_scc1 .LBB0_1763

; #define S_BARRIER() emu::block_barrier()
; #define WAIT_VM(n) do {} while (0)
; #define WAIT_LGKM(n) do {} while (0)
; #define SCHED_BARRIER() do {} while (0)
; #define S_BARRIER() __builtin_amdgcn_s_barrier()
; #define WAIT_VM(n) asm volatile("s_waitcnt vmcnt(" #n ")" ::: "memory")
; #define WAIT_LGKM(n) asm volatile("s_waitcnt lgkmcnt(" #n ")" ::: "memory")
; #define SCHED_BARRIER() __builtin_amdgcn_sched_barrier(0)
; #define PG8_STAGE(bufoff, gbase, voff) do { _Pragma("unroll") for (int _i = 0; _i < 2; ++_i) \
;         glds16(((const char*)(gbase) + (voff)[_i]), (lds + (bufoff) + ldsw + _i * 8192)); } while (0)
; #define PG8_STAGEA(bufoff, gptr, h, nx) do { _Pragma("unroll") for (int _i = 0; _i < 2; ++_i) { \
;         const unsigned _o = Sched::GATHER_A ? ((nx) ? goffN[h][_i] : goffC[h][_i]) : voffA[_i] + (unsigned)((h) * hstep); \
;         glds16(((const char*)(gptr) + _o), (lds + (bufoff) + ldsw + _i * 8192)); } } while (0)
; #define PG8_LDA(dst, b, h) do { _Pragma("unroll") for (int m = 0; m < 4; ++m) _Pragma("unroll") for (int k = 0; k < 2; ++k) dst[m][k] = *(const LAS bf16x8*)(lds + PG8_SA(b, h) + aoff + m * 2048 + k * 1024); } while (0)
; #define PG8_LDB(dst, b, h) do { _Pragma("unroll") for (int n = 0; n < 2; ++n) _Pragma("unroll") for (int k = 0; k < 2; ++k) dst[n][k] = *(const LAS bf16x8*)(lds + PG8_SB(b, h) + boff + n * 2048 + k * 1024); } while (0)
; #define PG8_MMA(ai, bj, At, Bt) do { SETPRIO(1); _Pragma("unroll") for (int m = 0; m < 4; ++m) _Pragma("unroll") for (int n = 0; n < 2; ++n) _Pragma("unroll") for (int k = 0; k < 2; ++k) \
;         acc[ai][bj][m][n] = mfma16(Bt[n][k], At[m][k], acc[ai][bj][m][n]); SETPRIO(0); } while (0)
; template <class Epi, class Sched>
; DEV void gemm_phase(LAS unsigned char* lds, const int K, const Sched& S, const Epi& E, const int wid, const int lane) {
;     ...
;             PG8_LDB(B0, 0, 0); PG8_LDB(B1, 0, 1); SCHED_BARRIER(); PG8_LDA(At, 0, 0); PG8_STAGEA(PG8_SA(1, 1), a1, 1, false);
;             WAIT_VM(8); WAIT_LGKM(0); S_BARRIER(); PG8_MMA(0, 0, At, B0); PG8_MMA(0, 1, At, B1); S_BARRIER(); SCHED_BARRIER();
;             PG8_LDA(At, 0, 1); PG8_STAGE(PG8_SB(0, 0), b2, voffB); PG8_STAGE(PG8_SB(0, 1), b2 + hstep, voffB); PG8_STAGEA(PG8_SA(0, 0), a2, 0, last);
;             WAIT_VM(8); WAIT_LGKM(0); S_BARRIER(); PG8_MMA(1, 0, At, B0); PG8_MMA(1, 1, At, B1); S_BARRIER(); SCHED_BARRIER();
.LBB0_1822:
	s_add_u32 s26, s24, 0x80
	s_addc_u32 s27, s25, 0
	s_add_i32 s54, 0, 0x10000
	s_cmp_eq_u32 s17, 28
	s_cselect_b32 s29, s19, s27
	s_cselect_b32 s28, s18, s26
	v_add_u32_e32 v144, s54, v148
	s_cselect_b32 s27, s21, s15
	s_cselect_b32 s26, s20, s13
	s_add_i32 s56, 0, 0x14000
	ds_read_b128 v[150:153], v144
	ds_read_b128 v[158:161], v144 offset:1024
	ds_read_b128 v[162:165], v144 offset:2048
	ds_read_b128 v[166:169], v144 offset:3072
	v_add_u32_e32 v144, s56, v148
	ds_read_b128 v[170:173], v144
	ds_read_b128 v[174:177], v144 offset:1024
	ds_read_b128 v[178:181], v144 offset:2048
	ds_read_b128 v[182:185], v144 offset:3072
	v_lshl_add_u64 v[144:145], s[24:25], 0, v[142:143]
	s_add_i32 m0, s43, 0xc000
	ds_read_b128 v[186:189], v157
	ds_read_b128 v[190:193], v157 offset:1024
	ds_read_b128 v[194:197], v157 offset:2048
	ds_read_b128 v[212:215], v157 offset:3072
	ds_read_b128 v[224:227], v157 offset:4096
	ds_read_b128 v[228:231], v157 offset:5120
	ds_read_b128 v[232:235], v157 offset:6144
	ds_read_b128 v[236:239], v157 offset:7168
	global_load_lds_dwordx4 v[144:145], off
	v_lshl_add_u64 v[144:145], s[24:25], 0, v[140:141]
	s_add_i32 m0, s43, 0xe000
	s_nop 0
	global_load_lds_dwordx4 v[144:145], off
	s_waitcnt vmcnt(8)
	s_waitcnt lgkmcnt(0)
	s_barrier
	s_setprio 1
	s_waitcnt lgkmcnt(0)
	v_mfma_f32_16x16x32_bf16 v[126:129], v[150:153], v[186:189], v[126:129]
	v_mfma_f32_16x16x32_bf16 v[122:125], v[162:165], v[186:189], v[122:125]
	v_mfma_f32_16x16x32_bf16 v[110:113], v[150:153], v[194:197], v[110:113]
	v_mfma_f32_16x16x32_bf16 v[106:109], v[162:165], v[194:197], v[106:109]
	v_mfma_f32_16x16x32_bf16 v[94:97], v[150:153], v[224:227], v[94:97]
	v_mfma_f32_16x16x32_bf16 v[90:93], v[162:165], v[224:227], v[90:93]
	v_mfma_f32_16x16x32_bf16 v[78:81], v[150:153], v[232:235], v[78:81]
	v_mfma_f32_16x16x32_bf16 v[74:77], v[162:165], v[232:235], v[74:77]
	v_mfma_f32_16x16x32_bf16 v[126:129], v[158:161], v[190:193], v[126:129]
	v_mfma_f32_16x16x32_bf16 v[122:125], v[166:169], v[190:193], v[122:125]
	v_mfma_f32_16x16x32_bf16 v[110:113], v[158:161], v[212:215], v[110:113]
	v_mfma_f32_16x16x32_bf16 v[106:109], v[166:169], v[212:215], v[106:109]
	v_mfma_f32_16x16x32_bf16 v[94:97], v[158:161], v[228:231], v[94:97]
	v_mfma_f32_16x16x32_bf16 v[90:93], v[166:169], v[228:231], v[90:93]
	v_mfma_f32_16x16x32_bf16 v[78:81], v[158:161], v[236:239], v[78:81]
	v_mfma_f32_16x16x32_bf16 v[74:77], v[166:169], v[236:239], v[74:77]
	s_setprio 0
	s_setprio 1
	v_mfma_f32_16x16x32_bf16 v[118:121], v[170:173], v[186:189], v[118:121]
	v_mfma_f32_16x16x32_bf16 v[114:117], v[178:181], v[186:189], v[114:117]
	v_mfma_f32_16x16x32_bf16 v[102:105], v[170:173], v[194:197], v[102:105]
	v_mfma_f32_16x16x32_bf16 v[98:101], v[178:181], v[194:197], v[98:101]
	v_mfma_f32_16x16x32_bf16 v[86:89], v[170:173], v[224:227], v[86:89]
	v_mfma_f32_16x16x32_bf16 v[82:85], v[178:181], v[224:227], v[82:85]
	v_mfma_f32_16x16x32_bf16 v[70:73], v[170:173], v[232:235], v[70:73]
	v_mfma_f32_16x16x32_bf16 v[66:69], v[178:181], v[232:235], v[66:69]
	v_mfma_f32_16x16x32_bf16 v[118:121], v[174:177], v[190:193], v[118:121]
	v_mfma_f32_16x16x32_bf16 v[114:117], v[182:185], v[190:193], v[114:117]
	v_mfma_f32_16x16x32_bf16 v[102:105], v[174:177], v[212:215], v[102:105]
	v_mfma_f32_16x16x32_bf16 v[98:101], v[182:185], v[212:215], v[98:101]
	v_mfma_f32_16x16x32_bf16 v[86:89], v[174:177], v[228:231], v[86:89]
	v_mfma_f32_16x16x32_bf16 v[82:85], v[182:185], v[228:231], v[82:85]
	v_mfma_f32_16x16x32_bf16 v[70:73], v[174:177], v[236:239], v[70:73]
	v_mfma_f32_16x16x32_bf16 v[66:69], v[182:185], v[236:239], v[66:69]
	s_setprio 0
	s_barrier
	s_add_i32 s54, s54, s36
	v_lshl_add_u64 v[144:145], s[26:27], 0, v[0:1]
	s_mov_b32 m0, s54
	ds_read_b128 v[186:189], v157 offset:16384
	ds_read_b128 v[190:193], v157 offset:17408
	ds_read_b128 v[194:197], v157 offset:18432
	ds_read_b128 v[212:215], v157 offset:19456
	ds_read_b128 v[224:227], v157 offset:20480
	ds_read_b128 v[228:231], v157 offset:21504
	ds_read_b128 v[232:235], v157 offset:22528
	ds_read_b128 v[236:239], v157 offset:23552
	global_load_lds_dwordx4 v[144:145], off
	s_add_i32 m0, s54, 0x2000
	s_add_u32 s54, s26, 0x80000
	v_lshl_add_u64 v[154:155], s[26:27], 0, v[130:131]
	s_addc_u32 s55, s27, 0
	s_add_i32 s56, s56, s36
	global_load_lds_dwordx4 v[154:155], off
	v_lshl_add_u64 v[198:199], s[54:55], 0, v[0:1]
	s_mov_b32 m0, s56
	v_lshl_add_u64 v[216:217], s[28:29], 0, v[132:133]
	global_load_lds_dwordx4 v[198:199], off
	v_lshl_add_u64 v[198:199], s[54:55], 0, v[130:131]
	s_add_i32 m0, s56, 0x2000
	s_nop 0
	global_load_lds_dwordx4 v[198:199], off
	v_lshl_add_u64 v[198:199], s[28:29], 0, v[134:135]
	s_mov_b32 m0, s43
	s_nop 0
	global_load_lds_dwordx4 v[198:199], off
	s_mov_b32 m0, s44
	s_nop 0
	global_load_lds_dwordx4 v[216:217], off
	s_waitcnt vmcnt(8)
	s_waitcnt lgkmcnt(0)
	s_barrier
	s_setprio 1
	s_waitcnt lgkmcnt(0)
	s_cmp_eq_u32 s53, 8
	s_cbranch_scc1 .Lg5_h1
; #define S_BARRIER() emu::block_barrier()
; #define WAIT_VM(n) do {} while (0)
; #define WAIT_LGKM(n) do {} while (0)
; #define SCHED_BARRIER() do {} while (0)
; #define S_BARRIER() __builtin_amdgcn_s_barrier()
; #define WAIT_VM(n) asm volatile("s_waitcnt vmcnt(" #n ")" ::: "memory")
; #define WAIT_LGKM(n) asm volatile("s_waitcnt lgkmcnt(" #n ")" ::: "memory")
; #define SCHED_BARRIER() __builtin_amdgcn_sched_barrier(0)
; #define PG8_STAGE(bufoff, gbase, voff) do { _Pragma("unroll") for (int _i = 0; _i < 2; ++_i) \
;         glds16(((const char*)(gbase) + (voff)[_i]), (lds + (bufoff) + ldsw + _i * 8192)); } while (0)
; #define PG8_STAGEA(bufoff, gptr, h, nx) do { _Pragma("unroll") for (int _i = 0; _i < 2; ++_i) { \
;         const unsigned _o = Sched::GATHER_A ? ((nx) ? goffN[h][_i] : goffC[h][_i]) : voffA[_i] + (unsigned)((h) * hstep); \
;         glds16(((const char*)(gptr) + _o), (lds + (bufoff) + ldsw + _i * 8192)); } } while (0)
; #define PG8_LDA(dst, b, h) do { _Pragma("unroll") for (int m = 0; m < 4; ++m) _Pragma("unroll") for (int k = 0; k < 2; ++k) dst[m][k] = *(const LAS bf16x8*)(lds + PG8_SA(b, h) + aoff + m * 2048 + k * 1024); } while (0)
; #define PG8_LDB(dst, b, h) do { _Pragma("unroll") for (int n = 0; n < 2; ++n) _Pragma("unroll") for (int k = 0; k < 2; ++k) dst[n][k] = *(const LAS bf16x8*)(lds + PG8_SB(b, h) + boff + n * 2048 + k * 1024); } while (0)
; #define PG8_MMA(ai, bj, At, Bt) do { SETPRIO(1); _Pragma("unroll") for (int m = 0; m < 4; ++m) _Pragma("unroll") for (int n = 0; n < 2; ++n) _Pragma("unroll") for (int k = 0; k < 2; ++k) \
;         acc[ai][bj][m][n] = mfma16(Bt[n][k], At[m][k], acc[ai][bj][m][n]); SETPRIO(0); } while (0)
; template <class Epi, class Sched>
; DEV void gemm_phase(LAS unsigned char* lds, const int K, const Sched& S, const Epi& E, const int wid, const int lane) {
;     ...
;             WAIT_VM(8); WAIT_LGKM(0); S_BARRIER(); PG8_MMA(1, 0, At, B0); PG8_MMA(1, 1, At, B1); S_BARRIER(); SCHED_BARRIER();
;             PG8_LDB(B0, 1, 0); PG8_LDB(B1, 1, 1); SCHED_BARRIER(); PG8_LDA(At, 1, 0); PG8_STAGEA(PG8_SA(0, 1), a2, 1, last);
;             WAIT_VM(8); WAIT_LGKM(0); S_BARRIER(); PG8_MMA(0, 0, At, B0); PG8_MMA(0, 1, At, B1); S_BARRIER(); SCHED_BARRIER();
;             PG8_LDA(At, 1, 1); PG8_STAGE(PG8_SB(1, 0), b3, voffB); PG8_STAGE(PG8_SB(1, 1), b3 + hstep, voffB); PG8_STAGEA(PG8_SA(1, 0), a3, 0, last);
	v_mfma_f32_16x16x32_bf16 v[62:65], v[150:153], v[186:189], v[62:65]
	v_mfma_f32_16x16x32_bf16 v[58:61], v[162:165], v[186:189], v[58:61]
	v_mfma_f32_16x16x32_bf16 v[46:49], v[150:153], v[194:197], v[46:49]
	v_mfma_f32_16x16x32_bf16 v[42:45], v[162:165], v[194:197], v[42:45]
	v_mfma_f32_16x16x32_bf16 v[30:33], v[150:153], v[224:227], v[30:33]
	v_mfma_f32_16x16x32_bf16 v[26:29], v[162:165], v[224:227], v[26:29]
	v_mfma_f32_16x16x32_bf16 v[14:17], v[150:153], v[232:235], v[14:17]
	v_mfma_f32_16x16x32_bf16 v[10:13], v[162:165], v[232:235], v[10:13]
	v_mfma_f32_16x16x32_bf16 v[62:65], v[158:161], v[190:193], v[62:65]
	v_mfma_f32_16x16x32_bf16 v[58:61], v[166:169], v[190:193], v[58:61]
	v_mfma_f32_16x16x32_bf16 v[46:49], v[158:161], v[212:215], v[46:49]
	v_mfma_f32_16x16x32_bf16 v[42:45], v[166:169], v[212:215], v[42:45]
	v_mfma_f32_16x16x32_bf16 v[30:33], v[158:161], v[228:231], v[30:33]
	v_mfma_f32_16x16x32_bf16 v[26:29], v[166:169], v[228:231], v[26:29]
	v_mfma_f32_16x16x32_bf16 v[14:17], v[158:161], v[236:239], v[14:17]
	v_mfma_f32_16x16x32_bf16 v[10:13], v[166:169], v[236:239], v[10:13]
	s_setprio 0
	s_setprio 1
	v_mfma_f32_16x16x32_bf16 v[54:57], v[170:173], v[186:189], v[54:57]
	v_mfma_f32_16x16x32_bf16 v[50:53], v[178:181], v[186:189], v[50:53]
	v_mfma_f32_16x16x32_bf16 v[38:41], v[170:173], v[194:197], v[38:41]
	v_mfma_f32_16x16x32_bf16 v[34:37], v[178:181], v[194:197], v[34:37]
	v_mfma_f32_16x16x32_bf16 v[22:25], v[170:173], v[224:227], v[22:25]
	v_mfma_f32_16x16x32_bf16 v[18:21], v[178:181], v[224:227], v[18:21]
	v_mfma_f32_16x16x32_bf16 v[6:9], v[170:173], v[232:235], v[6:9]
	v_mfma_f32_16x16x32_bf16 v[2:5], v[178:181], v[232:235], v[2:5]
	v_mfma_f32_16x16x32_bf16 v[54:57], v[174:177], v[190:193], v[54:57]
	v_mfma_f32_16x16x32_bf16 v[50:53], v[182:185], v[190:193], v[50:53]
	v_mfma_f32_16x16x32_bf16 v[38:41], v[174:177], v[212:215], v[38:41]
	v_mfma_f32_16x16x32_bf16 v[34:37], v[182:185], v[212:215], v[34:37]
	v_mfma_f32_16x16x32_bf16 v[22:25], v[174:177], v[228:231], v[22:25]
	v_mfma_f32_16x16x32_bf16 v[18:21], v[182:185], v[228:231], v[18:21]
	v_mfma_f32_16x16x32_bf16 v[6:9], v[174:177], v[236:239], v[6:9]
	v_mfma_f32_16x16x32_bf16 v[2:5], v[182:185], v[236:239], v[2:5]
.Lg5_h1:
	s_setprio 0
	s_barrier
	s_add_i32 s54, 0, 0x18000
	s_add_i32 s55, 0, 0x1c000
	v_add_u32_e32 v166, s54, v148
	v_add_u32_e32 v182, s55, v148
	ds_read_b128 v[150:153], v166
	ds_read_b128 v[158:161], v166 offset:1024
	ds_read_b128 v[162:165], v166 offset:2048
	ds_read_b128 v[166:169], v166 offset:3072
	ds_read_b128 v[170:173], v182
	ds_read_b128 v[174:177], v182 offset:1024
	ds_read_b128 v[178:181], v182 offset:2048
	ds_read_b128 v[182:185], v182 offset:3072
	s_mov_b32 m0, s45
	v_lshl_add_u64 v[218:219], s[28:29], 0, v[136:137]
	ds_read_b128 v[186:189], v157 offset:32768
	ds_read_b128 v[190:193], v157 offset:33792
	ds_read_b128 v[194:197], v157 offset:34816
	ds_read_b128 v[212:215], v157 offset:35840
	ds_read_b128 v[224:227], v157 offset:36864
	ds_read_b128 v[228:231], v157 offset:37888
	ds_read_b128 v[232:235], v157 offset:38912
	ds_read_b128 v[236:239], v157 offset:39936
	global_load_lds_dwordx4 v[218:219], off
	v_lshl_add_u64 v[218:219], s[28:29], 0, v[138:139]
	s_mov_b32 m0, s46
	s_nop 0
	global_load_lds_dwordx4 v[218:219], off
	s_waitcnt vmcnt(8)
	s_waitcnt lgkmcnt(0)
	s_barrier
	s_setprio 1
	s_waitcnt lgkmcnt(0)
	v_mfma_f32_16x16x32_bf16 v[126:129], v[150:153], v[186:189], v[126:129]
	v_mfma_f32_16x16x32_bf16 v[122:125], v[162:165], v[186:189], v[122:125]
	v_mfma_f32_16x16x32_bf16 v[110:113], v[150:153], v[194:197], v[110:113]
	v_mfma_f32_16x16x32_bf16 v[106:109], v[162:165], v[194:197], v[106:109]
	v_mfma_f32_16x16x32_bf16 v[94:97], v[150:153], v[224:227], v[94:97]
	v_mfma_f32_16x16x32_bf16 v[90:93], v[162:165], v[224:227], v[90:93]
	v_mfma_f32_16x16x32_bf16 v[78:81], v[150:153], v[232:235], v[78:81]
	v_mfma_f32_16x16x32_bf16 v[74:77], v[162:165], v[232:235], v[74:77]
	v_mfma_f32_16x16x32_bf16 v[126:129], v[158:161], v[190:193], v[126:129]
	v_mfma_f32_16x16x32_bf16 v[122:125], v[166:169], v[190:193], v[122:125]
	v_mfma_f32_16x16x32_bf16 v[110:113], v[158:161], v[212:215], v[110:113]
	v_mfma_f32_16x16x32_bf16 v[106:109], v[166:169], v[212:215], v[106:109]
	v_mfma_f32_16x16x32_bf16 v[94:97], v[158:161], v[228:231], v[94:97]
	v_mfma_f32_16x16x32_bf16 v[90:93], v[166:169], v[228:231], v[90:93]
	v_mfma_f32_16x16x32_bf16 v[78:81], v[158:161], v[236:239], v[78:81]
	v_mfma_f32_16x16x32_bf16 v[74:77], v[166:169], v[236:239], v[74:77]
	s_setprio 0
	s_setprio 1
	v_mfma_f32_16x16x32_bf16 v[118:121], v[170:173], v[186:189], v[118:121]
	v_mfma_f32_16x16x32_bf16 v[114:117], v[178:181], v[186:189], v[114:117]
	v_mfma_f32_16x16x32_bf16 v[102:105], v[170:173], v[194:197], v[102:105]
	v_mfma_f32_16x16x32_bf16 v[98:101], v[178:181], v[194:197], v[98:101]
	v_mfma_f32_16x16x32_bf16 v[86:89], v[170:173], v[224:227], v[86:89]
	v_mfma_f32_16x16x32_bf16 v[82:85], v[178:181], v[224:227], v[82:85]
	v_mfma_f32_16x16x32_bf16 v[70:73], v[170:173], v[232:235], v[70:73]
	v_mfma_f32_16x16x32_bf16 v[66:69], v[178:181], v[232:235], v[66:69]
	v_mfma_f32_16x16x32_bf16 v[118:121], v[174:177], v[190:193], v[118:121]
	v_mfma_f32_16x16x32_bf16 v[114:117], v[182:185], v[190:193], v[114:117]
	v_mfma_f32_16x16x32_bf16 v[102:105], v[174:177], v[212:215], v[102:105]
	v_mfma_f32_16x16x32_bf16 v[98:101], v[182:185], v[212:215], v[98:101]
	v_mfma_f32_16x16x32_bf16 v[86:89], v[174:177], v[228:231], v[86:89]
	v_mfma_f32_16x16x32_bf16 v[82:85], v[182:185], v[228:231], v[82:85]
	v_mfma_f32_16x16x32_bf16 v[70:73], v[174:177], v[236:239], v[70:73]
	v_mfma_f32_16x16x32_bf16 v[66:69], v[182:185], v[236:239], v[66:69]
	s_setprio 0
	s_barrier
; #define S_BARRIER() emu::block_barrier()
; #define WAIT_VM(n) do {} while (0)
; #define WAIT_LGKM(n) do {} while (0)
; #define SCHED_BARRIER() do {} while (0)
; #define S_BARRIER() __builtin_amdgcn_s_barrier()
; #define WAIT_VM(n) asm volatile("s_waitcnt vmcnt(" #n ")" ::: "memory")
; #define WAIT_LGKM(n) asm volatile("s_waitcnt lgkmcnt(" #n ")" ::: "memory")
; #define SCHED_BARRIER() __builtin_amdgcn_sched_barrier(0)
; #define PG8_STAGE(bufoff, gbase, voff) do { _Pragma("unroll") for (int _i = 0; _i < 2; ++_i) \
;         glds16(((const char*)(gbase) + (voff)[_i]), (lds + (bufoff) + ldsw + _i * 8192)); } while (0)
; #define PG8_STAGEA(bufoff, gptr, h, nx) do { _Pragma("unroll") for (int _i = 0; _i < 2; ++_i) { \
;         const unsigned _o = Sched::GATHER_A ? ((nx) ? goffN[h][_i] : goffC[h][_i]) : voffA[_i] + (unsigned)((h) * hstep); \
;         glds16(((const char*)(gptr) + _o), (lds + (bufoff) + ldsw + _i * 8192)); } } while (0)
; #define PG8_LDA(dst, b, h) do { _Pragma("unroll") for (int m = 0; m < 4; ++m) _Pragma("unroll") for (int k = 0; k < 2; ++k) dst[m][k] = *(const LAS bf16x8*)(lds + PG8_SA(b, h) + aoff + m * 2048 + k * 1024); } while (0)
; #define PG8_MMA(ai, bj, At, Bt) do { SETPRIO(1); _Pragma("unroll") for (int m = 0; m < 4; ++m) _Pragma("unroll") for (int n = 0; n < 2; ++n) _Pragma("unroll") for (int k = 0; k < 2; ++k) \
;         acc[ai][bj][m][n] = mfma16(Bt[n][k], At[m][k], acc[ai][bj][m][n]); SETPRIO(0); } while (0)
; template <class Epi, class Sched>
; DEV void gemm_phase(LAS unsigned char* lds, const int K, const Sched& S, const Epi& E, const int wid, const int lane) {
;     ...
;             PG8_LDA(At, 1, 1); PG8_STAGE(PG8_SB(1, 0), b3, voffB); PG8_STAGE(PG8_SB(1, 1), b3 + hstep, voffB); PG8_STAGEA(PG8_SA(1, 0), a3, 0, last);
;             WAIT_VM(8); WAIT_LGKM(0); S_BARRIER(); PG8_MMA(1, 0, At, B0); PG8_MMA(1, 1, At, B1); S_BARRIER(); SCHED_BARRIER();
;         }
	s_add_i32 s28, s54, s36
	v_lshl_add_u64 v[144:145], v[144:145], 0, s[90:91]
	s_mov_b32 m0, s28
	ds_read_b128 v[186:189], v157 offset:49152
	ds_read_b128 v[190:193], v157 offset:50176
	ds_read_b128 v[194:197], v157 offset:51200
	ds_read_b128 v[212:215], v157 offset:52224
	ds_read_b128 v[224:227], v157 offset:53248
	ds_read_b128 v[228:231], v157 offset:54272
	ds_read_b128 v[232:235], v157 offset:55296
	ds_read_b128 v[236:239], v157 offset:56320
	global_load_lds_dwordx4 v[144:145], off
	s_add_i32 m0, s28, 0x2000
	s_add_u32 s26, s26, 0x80080
	v_lshl_add_u64 v[144:145], v[154:155], 0, s[90:91]
	s_addc_u32 s27, s27, 0
	s_add_i32 s28, s55, s36
	global_load_lds_dwordx4 v[144:145], off
	v_lshl_add_u64 v[144:145], s[26:27], 0, v[0:1]
	s_mov_b32 m0, s28
	s_nop 0
	global_load_lds_dwordx4 v[144:145], off
	v_lshl_add_u64 v[144:145], s[26:27], 0, v[130:131]
	s_add_i32 m0, s28, 0x2000
	s_nop 0
	global_load_lds_dwordx4 v[144:145], off
	v_lshl_add_u64 v[144:145], v[198:199], 0, s[90:91]
	s_mov_b32 m0, s47
	s_nop 0
	global_load_lds_dwordx4 v[144:145], off
	v_lshl_add_u64 v[144:145], v[216:217], 0, s[90:91]
	s_mov_b32 m0, s48
	s_nop 0
	global_load_lds_dwordx4 v[144:145], off
	s_waitcnt vmcnt(8)
	s_waitcnt lgkmcnt(0)
	s_barrier
	s_setprio 1
	s_waitcnt lgkmcnt(0)
	s_cmp_eq_u32 s53, 8
	s_cbranch_scc1 .Lg5_h3
	v_mfma_f32_16x16x32_bf16 v[62:65], v[150:153], v[186:189], v[62:65]
	v_mfma_f32_16x16x32_bf16 v[58:61], v[162:165], v[186:189], v[58:61]
	v_mfma_f32_16x16x32_bf16 v[46:49], v[150:153], v[194:197], v[46:49]
	v_mfma_f32_16x16x32_bf16 v[42:45], v[162:165], v[194:197], v[42:45]
	v_mfma_f32_16x16x32_bf16 v[30:33], v[150:153], v[224:227], v[30:33]
	v_mfma_f32_16x16x32_bf16 v[26:29], v[162:165], v[224:227], v[26:29]
	v_mfma_f32_16x16x32_bf16 v[14:17], v[150:153], v[232:235], v[14:17]
	v_mfma_f32_16x16x32_bf16 v[10:13], v[162:165], v[232:235], v[10:13]
	v_mfma_f32_16x16x32_bf16 v[62:65], v[158:161], v[190:193], v[62:65]
	v_mfma_f32_16x16x32_bf16 v[58:61], v[166:169], v[190:193], v[58:61]
	v_mfma_f32_16x16x32_bf16 v[46:49], v[158:161], v[212:215], v[46:49]
	v_mfma_f32_16x16x32_bf16 v[42:45], v[166:169], v[212:215], v[42:45]
	v_mfma_f32_16x16x32_bf16 v[30:33], v[158:161], v[228:231], v[30:33]
	v_mfma_f32_16x16x32_bf16 v[26:29], v[166:169], v[228:231], v[26:29]
	v_mfma_f32_16x16x32_bf16 v[14:17], v[158:161], v[236:239], v[14:17]
	v_mfma_f32_16x16x32_bf16 v[10:13], v[166:169], v[236:239], v[10:13]
	s_setprio 0
	s_setprio 1
	v_mfma_f32_16x16x32_bf16 v[54:57], v[170:173], v[186:189], v[54:57]
	v_mfma_f32_16x16x32_bf16 v[50:53], v[178:181], v[186:189], v[50:53]
	v_mfma_f32_16x16x32_bf16 v[38:41], v[170:173], v[194:197], v[38:41]
	v_mfma_f32_16x16x32_bf16 v[34:37], v[178:181], v[194:197], v[34:37]
	v_mfma_f32_16x16x32_bf16 v[22:25], v[170:173], v[224:227], v[22:25]
	v_mfma_f32_16x16x32_bf16 v[18:21], v[178:181], v[224:227], v[18:21]
	v_mfma_f32_16x16x32_bf16 v[6:9], v[170:173], v[232:235], v[6:9]
	v_mfma_f32_16x16x32_bf16 v[2:5], v[178:181], v[232:235], v[2:5]
	v_mfma_f32_16x16x32_bf16 v[54:57], v[174:177], v[190:193], v[54:57]
	v_mfma_f32_16x16x32_bf16 v[50:53], v[182:185], v[190:193], v[50:53]
	v_mfma_f32_16x16x32_bf16 v[38:41], v[174:177], v[212:215], v[38:41]
	v_mfma_f32_16x16x32_bf16 v[34:37], v[182:185], v[212:215], v[34:37]
	v_mfma_f32_16x16x32_bf16 v[22:25], v[174:177], v[228:231], v[22:25]
	v_mfma_f32_16x16x32_bf16 v[18:21], v[182:185], v[228:231], v[18:21]
	v_mfma_f32_16x16x32_bf16 v[6:9], v[174:177], v[236:239], v[6:9]
	v_mfma_f32_16x16x32_bf16 v[2:5], v[182:185], v[236:239], v[2:5]
.Lg5_h3:
	s_setprio 0
	s_barrier
	s_add_i32 s17, s17, 2
	s_add_u32 s13, s13, 0x100
	s_addc_u32 s15, s15, 0
	s_add_u32 s24, s24, 0x100
	s_addc_u32 s25, s25, 0
	s_cmp_gt_u32 s17, 29
	s_cbranch_scc0 .LBB0_1822
	s_and_b64 vcc, exec, s[10:11]
	s_cbranch_vccz .LBB0_1825
	s_barrier
